# attention loop edge: the rare score-shift block moved out of line so the per-tile uniform branch between QK^T and PV falls through (strategy 9)
# speedup vs baseline: 1.0143x; 1.0004x over previous
; #define SBAR() __builtin_amdgcn_sched_barrier(0)
; __device__ __forceinline__ void finishSM(f32x16& p0, f32x16& p1, float alpha, float& l_reg, bf16x8& pa0, bf16x8& pa1, bf16x8& pa2, bf16x8& pa3) {
;     for (int r = 0; r < 16; ++r) p1[r] = __builtin_amdgcn_exp2f(p1[r]);
;     float ps = 0; for (int r = 0; r < 16; ++r) ps += p0[r]; for (int r = 0; r < 16; ++r) ps += p1[r];
;     { auto rr = __builtin_amdgcn_permlane32_swap(__float_as_uint(ps), __float_as_uint(ps), false, false);
;       ps = __uint_as_float(rr[0]) + __uint_as_float(rr[1]); }
;     l_reg = l_reg * alpha + ps;
;     ...
;     PK4(p0, 0, pa0); PK4(p0, 8, pa1); PK4(p1, 0, pa2); PK4(p1, 8, pa3);
;     ...
; }
; __device__ __forceinline__ void qkt(f32x16& p0, f32x16& p1, const bf16_t* Ks, const bf16x8* qr, int r32, int hi) {
;     p0 = f32x16{}; p1 = f32x16{};
;     for (int d0 = 0; d0 < 8; ++d0) { int cb = (d0 * 16 + hi * 8) * 2;
;         bf16x8 b0 = *reinterpret_cast<const bf16x8*>((const char*)Ks + KSWZ(r32, cb));
;         bf16x8 b1 = *reinterpret_cast<const bf16x8*>((const char*)Ks + KSWZ(32 + r32, cb));
;         p0 = __builtin_amdgcn_mfma_f32_32x32x16_bf16(b0, qr[d0], p0, 0, 0, 0);
;         p1 = __builtin_amdgcn_mfma_f32_32x32x16_bf16(b1, qr[d0], p1, 0, 0, 0); }
; }
; template <int D0> __device__ __forceinline__ void pv_one(f32x16& od, int vb, bf16x8 pa0, bf16x8 pa1, bf16x8 pa2, bf16x8 pa3) {
;     const s16x4 l0 = tr_read<v_rd_off(D0, 0, 0)>(vb), h0 = tr_read<v_rd_off(D0, 0, 1)>(vb), l1 = tr_read<v_rd_off(D0, 1, 0)>(vb), h1 = tr_read<v_rd_off(D0, 1, 1)>(vb);
;     const s16x4 l2 = tr_read<v_rd_off(D0, 2, 0)>(vb), h2 = tr_read<v_rd_off(D0, 2, 1)>(vb), l3 = tr_read<v_rd_off(D0, 3, 0)>(vb), h3 = tr_read<v_rd_off(D0, 3, 1)>(vb);
;     asm volatile("s_waitcnt lgkmcnt(0)" ::: "memory"); SBAR();
.LBB0_490:
	ds_read_b128 v[236:239], v211 offset:49152
	ds_read_b128 v[240:243], v211 offset:57344
	ds_read_b128 v[244:247], v212 offset:49152
	ds_read_b128 v[248:251], v212 offset:57344
	v_add_f32_e32 v219, v233, v235
	v_cvt_pk_bf16_f32 v160, v233, v235
	v_add_f32_e32 v219, v231, v219
	s_waitcnt lgkmcnt(3)
	v_mfma_f32_32x32x16_bf16 v[96:111], v[236:239], v[116:119], 0
	v_cvt_pk_bf16_f32 v161, v231, v234
	v_add_f32_e32 v219, v234, v219
	v_cvt_pk_bf16_f32 v162, v230, v232
	v_add_f32_e32 v219, v230, v219
	v_cvt_pk_bf16_f32 v163, v228, v229
	s_waitcnt lgkmcnt(2)
	v_mfma_f32_32x32x16_bf16 v[80:95], v[240:243], v[116:119], 0
	ds_read_b128 v[236:239], v213 offset:49152
	ds_read_b128 v[240:243], v213 offset:57344
	v_add_f32_e32 v219, v232, v219
	v_cvt_pk_bf16_f32 v164, v225, v227
	v_add_f32_e32 v219, v228, v219
	v_cvt_pk_bf16_f32 v165, v224, v226
	v_add_f32_e32 v219, v229, v219
	s_waitcnt lgkmcnt(3)
	v_mfma_f32_32x32x16_bf16 v[96:111], v[244:247], v[124:127], v[96:111]
	v_cvt_pk_bf16_f32 v166, v221, v223
	v_add_f32_e32 v219, v225, v219
	v_cvt_pk_bf16_f32 v167, v181, v222
	v_add_f32_e32 v219, v227, v219
	s_waitcnt lgkmcnt(2)
	v_mfma_f32_32x32x16_bf16 v[80:95], v[248:251], v[124:127], v[80:95]
	ds_read_b128 v[244:247], v214 offset:49152
	ds_read_b128 v[248:251], v214 offset:57344
	v_cvt_pk_bf16_f32 v168, v64, v65
	v_add_f32_e32 v219, v224, v219
	v_cvt_pk_bf16_f32 v169, v66, v67
	v_add_f32_e32 v219, v226, v219
	s_waitcnt lgkmcnt(3)
	v_mfma_f32_32x32x16_bf16 v[96:111], v[236:239], v[112:115], v[96:111]
	v_cvt_pk_bf16_f32 v170, v68, v69
	v_add_f32_e32 v219, v221, v219
	v_cvt_pk_bf16_f32 v171, v70, v71
	v_add_f32_e32 v219, v223, v219
	s_waitcnt lgkmcnt(2)
	v_mfma_f32_32x32x16_bf16 v[80:95], v[240:243], v[112:115], v[80:95]
	ds_read_b128 v[236:239], v215 offset:49152
	ds_read_b128 v[240:243], v215 offset:57344
	v_cvt_pk_bf16_f32 v172, v72, v73
	v_add_f32_e32 v219, v181, v219
	v_cvt_pk_bf16_f32 v173, v74, v75
	v_add_f32_e32 v219, v222, v219
	s_waitcnt lgkmcnt(3)
	v_mfma_f32_32x32x16_bf16 v[96:111], v[244:247], v[120:123], v[96:111]
	v_cvt_pk_bf16_f32 v174, v76, v77
	v_add_f32_e32 v219, v64, v219
	v_cvt_pk_bf16_f32 v175, v78, v79
	v_add_f32_e32 v219, v65, v219
	s_waitcnt lgkmcnt(2)
	v_mfma_f32_32x32x16_bf16 v[80:95], v[248:251], v[120:123], v[80:95]
	ds_read_b128 v[244:247], v216 offset:49152
	ds_read_b128 v[248:251], v216 offset:57344
	v_permlane32_swap_b32_e32 v160, v162
	v_add_f32_e32 v219, v66, v219
	s_waitcnt lgkmcnt(3)
	v_mfma_f32_32x32x16_bf16 v[96:111], v[236:239], v[132:135], v[96:111]
	v_permlane32_swap_b32_e32 v161, v163
	v_add_f32_e32 v219, v67, v219
	v_permlane32_swap_b32_e32 v164, v166
	s_waitcnt lgkmcnt(2)
	v_mfma_f32_32x32x16_bf16 v[80:95], v[240:243], v[132:135], v[80:95]
	ds_read_b128 v[236:239], v217 offset:49152
	ds_read_b128 v[240:243], v217 offset:57344
	v_add_f32_e32 v219, v68, v219
	v_permlane32_swap_b32_e32 v165, v167
	v_add_f32_e32 v219, v69, v219
	s_waitcnt lgkmcnt(3)
	v_mfma_f32_32x32x16_bf16 v[96:111], v[244:247], v[140:143], v[96:111]
	v_permlane32_swap_b32_e32 v168, v170
	v_add_f32_e32 v219, v70, v219
	s_waitcnt lgkmcnt(2)
	v_mfma_f32_32x32x16_bf16 v[80:95], v[248:251], v[140:143], v[80:95]
	ds_read_b128 v[244:247], v218 offset:49152
	ds_read_b128 v[248:251], v218 offset:57344
	v_permlane32_swap_b32_e32 v169, v171
	v_add_f32_e32 v219, v71, v219
	v_permlane32_swap_b32_e32 v172, v174
	s_waitcnt lgkmcnt(3)
	v_mfma_f32_32x32x16_bf16 v[96:111], v[236:239], v[128:131], v[96:111]
	v_add_f32_e32 v219, v72, v219
	v_permlane32_swap_b32_e32 v173, v175
	v_add_f32_e32 v219, v73, v219
	s_waitcnt lgkmcnt(2)
	v_mfma_f32_32x32x16_bf16 v[80:95], v[240:243], v[128:131], v[80:95]
	ds_read_b64_tr_b16 v[236:237], v206 offset:0
	ds_read_b64_tr_b16 v[238:239], v206 offset:2048
	ds_read_b64_tr_b16 v[240:241], v206 offset:4096
	ds_read_b64_tr_b16 v[242:243], v206 offset:6144
	v_add_f32_e32 v219, v74, v219
	v_add_f32_e32 v219, v75, v219
	v_add_f32_e32 v219, v76, v219
	v_add_f32_e32 v219, v77, v219
	s_waitcnt lgkmcnt(5)
	v_mfma_f32_32x32x16_bf16 v[96:111], v[244:247], v[136:139], v[96:111]
	v_add_f32_e32 v219, v78, v219
	v_add_f32_e32 v219, v79, v219
	v_mov_b32_e32 v220, v219
	s_nop 1
	s_waitcnt lgkmcnt(4)
	v_mfma_f32_32x32x16_bf16 v[80:95], v[248:251], v[136:139], v[80:95]
	v_permlane32_swap_b32_e32 v219, v220
	v_add_f32_e32 v219, v219, v220
	v_add_f32_e32 v204, v204, v219
	ds_read_b64_tr_b16 v[244:245], v206 offset:8192
	ds_read_b64_tr_b16 v[246:247], v206 offset:10240
	ds_read_b64_tr_b16 v[248:249], v206 offset:12288
	ds_read_b64_tr_b16 v[250:251], v206 offset:14336
	s_and_b64 vcc, exec, s[6:7]
	s_cbranch_vccz .Lat2_shift_A
; #define SBAR() __builtin_amdgcn_sched_barrier(0)
; #define SLOAD(i, k0) do { sr_[i].vs0 = LD8(&Vh[(long)((k0) + sr) * LDK + sc]); sr_[i].vs1 = LD8(&Vh[(long)((k0) + 32 + sr) * LDK + sc]); \
;     sr_[i].ks0 = LD8(&Kh[(long)((k0) + sr) * LDK + sc]); sr_[i].ks1 = LD8(&Kh[(long)((k0) + 32 + sr) * LDK + sc]); } while (0)
; #define SWRITE(b, i) do { *(bf16x8*)((char*)V_lds + (b) * SHM_V + vst0) = sr_[i].vs0;          \
;     *(bf16x8*)((char*)V_lds + (b) * SHM_V + vst1) = sr_[i].vs1; int kc = sc * 2;               \
;     *(bf16x8*)((char*)K_lds + (b) * SHM_K + KSWZ(sr, kc)) = sr_[i].ks0;                       \
;     *(bf16x8*)((char*)K_lds + (b) * SHM_K + KSWZ(32 + sr, kc)) = sr_[i].ks1; } while (0)
; #define SWAIT() asm volatile("s_waitcnt vmcnt(4)" ::: "memory")
; template <int D0> __device__ __forceinline__ void pv_one(f32x16& od, int vb, bf16x8 pa0, bf16x8 pa1, bf16x8 pa2, bf16x8 pa3) {
;     const s16x4 l0 = tr_read<v_rd_off(D0, 0, 0)>(vb), h0 = tr_read<v_rd_off(D0, 0, 1)>(vb), l1 = tr_read<v_rd_off(D0, 1, 0)>(vb), h1 = tr_read<v_rd_off(D0, 1, 1)>(vb);
;     const s16x4 l2 = tr_read<v_rd_off(D0, 2, 0)>(vb), h2 = tr_read<v_rd_off(D0, 2, 1)>(vb), l3 = tr_read<v_rd_off(D0, 3, 0)>(vb), h3 = tr_read<v_rd_off(D0, 3, 1)>(vb);
;     asm volatile("s_waitcnt lgkmcnt(0)" ::: "memory"); SBAR();
;     ...
;     od = __builtin_amdgcn_mfma_f32_32x32x16_bf16(pa0, PK(l0, h0), od, 0, 0, 0);
;     od = __builtin_amdgcn_mfma_f32_32x32x16_bf16(pa1, PK(l1, h1), od, 0, 0, 0);
;     od = __builtin_amdgcn_mfma_f32_32x32x16_bf16(pa2, PK(l2, h2), od, 0, 0, 0);
;     od = __builtin_amdgcn_mfma_f32_32x32x16_bf16(pa3, PK(l3, h3), od, 0, 0, 0);
; __device__ __forceinline__ void attn_body(const bf16_t* __restrict__ Qb, const bf16_t* __restrict__ Kh, const bf16_t* __restrict__ Vh, const bf16_t* __restrict__ Zb, ...
;     ...
;         SLOAD(SO, (j + 2) * KVBLK); SBAR();
;         pv_d0(o, vb0, pa0, pa1, pa2, pa3); partialSM(pB0, pB1, negBC);
;         __syncthreads(); SWAIT(); SWRITE(0, SE);
;         __syncthreads();
.Lat2_noshift_A:
	s_waitcnt lgkmcnt(6)
	v_mfma_f32_32x32x16_bf16 v[0:15], v[160:163], v[236:239], v[0:15]
	ds_read_b64_tr_b16 v[236:237], v206 offset:512
	ds_read_b64_tr_b16 v[238:239], v206 offset:2560
	s_waitcnt lgkmcnt(6)
	v_mfma_f32_32x32x16_bf16 v[0:15], v[164:167], v[240:243], v[0:15]
	ds_read_b64_tr_b16 v[240:241], v206 offset:4608
	ds_read_b64_tr_b16 v[242:243], v206 offset:6656
	s_waitcnt vmcnt(0)
	ds_write_b128 v209, v[148:151] offset:32768
	v_exp_f32_e32 v181, v96
	v_exp_f32_e32 v221, v97
	s_waitcnt lgkmcnt(7)
	v_mfma_f32_32x32x16_bf16 v[0:15], v[168:171], v[244:247], v[0:15]
	ds_read_b64_tr_b16 v[244:245], v206 offset:8704
	ds_read_b64_tr_b16 v[246:247], v206 offset:10752
	ds_write_b128 v210, v[152:155] offset:32768
	v_exp_f32_e32 v222, v98
	v_exp_f32_e32 v223, v99
	s_waitcnt lgkmcnt(8)
	v_mfma_f32_32x32x16_bf16 v[0:15], v[172:175], v[248:251], v[0:15]
	ds_read_b64_tr_b16 v[248:249], v206 offset:12800
	ds_read_b64_tr_b16 v[250:251], v206 offset:14848
	ds_write_b128 v252, v[144:147] offset:16384
	v_exp_f32_e32 v224, v100
	v_exp_f32_e32 v225, v101
	s_waitcnt lgkmcnt(9)
	v_mfma_f32_32x32x16_bf16 v[16:31], v[160:163], v[236:239], v[16:31]
	ds_read_b64_tr_b16 v[236:237], v206 offset:1024
	ds_read_b64_tr_b16 v[238:239], v206 offset:3072
	ds_write_b128 v253, v[156:159] offset:16384
	v_exp_f32_e32 v226, v102
	v_exp_f32_e32 v227, v103
	s_waitcnt lgkmcnt(10)
	v_mfma_f32_32x32x16_bf16 v[16:31], v[164:167], v[240:243], v[16:31]
	ds_read_b64_tr_b16 v[240:241], v206 offset:5120
	ds_read_b64_tr_b16 v[242:243], v206 offset:7168
	v_exp_f32_e32 v228, v104
	v_exp_f32_e32 v229, v105
	s_waitcnt lgkmcnt(9)
	v_mfma_f32_32x32x16_bf16 v[16:31], v[168:171], v[244:247], v[16:31]
	ds_read_b64_tr_b16 v[244:245], v206 offset:9216
	ds_read_b64_tr_b16 v[246:247], v206 offset:11264
	v_lshl_add_u64 v[144:145], v[190:191], 0, s[98:99]
	global_load_dwordx4 v[156:159], v[190:191], off
	global_load_dwordx4 v[144:147], v[144:145], off
	v_exp_f32_e32 v230, v106
	v_exp_f32_e32 v231, v107
	s_waitcnt lgkmcnt(8)
	v_mfma_f32_32x32x16_bf16 v[16:31], v[172:175], v[248:251], v[16:31]
	ds_read_b64_tr_b16 v[248:249], v206 offset:13312
	ds_read_b64_tr_b16 v[250:251], v206 offset:15360
	v_exp_f32_e32 v232, v108
	v_exp_f32_e32 v233, v109
	s_waitcnt lgkmcnt(7)
	v_mfma_f32_32x32x16_bf16 v[32:47], v[160:163], v[236:239], v[32:47]
	ds_read_b64_tr_b16 v[236:237], v206 offset:1536
	ds_read_b64_tr_b16 v[238:239], v206 offset:3584
	v_lshl_add_u64 v[190:191], v[190:191], 0, s[100:101]
	v_lshl_add_u64 v[148:149], v[190:191], 0, s[98:99]
	global_load_dwordx4 v[152:155], v[190:191], off offset:-512
	global_load_dwordx4 v[148:151], v[148:149], off offset:-512
	v_exp_f32_e32 v234, v110
	v_exp_f32_e32 v235, v111
	s_waitcnt lgkmcnt(6)
	v_mfma_f32_32x32x16_bf16 v[32:47], v[164:167], v[240:243], v[32:47]
	ds_read_b64_tr_b16 v[240:241], v206 offset:5632
	ds_read_b64_tr_b16 v[242:243], v206 offset:7680
	v_exp_f32_e32 v80, v80
	v_exp_f32_e32 v81, v81
	s_waitcnt lgkmcnt(6)
	v_mfma_f32_32x32x16_bf16 v[32:47], v[168:171], v[244:247], v[32:47]
	ds_read_b64_tr_b16 v[244:245], v206 offset:9728
	ds_read_b64_tr_b16 v[246:247], v206 offset:11776
	v_exp_f32_e32 v82, v82
	v_exp_f32_e32 v83, v83
	s_waitcnt lgkmcnt(6)
	v_mfma_f32_32x32x16_bf16 v[32:47], v[172:175], v[248:251], v[32:47]
	ds_read_b64_tr_b16 v[248:249], v206 offset:13824
	ds_read_b64_tr_b16 v[250:251], v206 offset:15872
	v_exp_f32_e32 v84, v84
	v_exp_f32_e32 v85, v85
	s_waitcnt lgkmcnt(6)
	v_mfma_f32_32x32x16_bf16 v[48:63], v[160:163], v[236:239], v[48:63]
	v_exp_f32_e32 v86, v86
	v_exp_f32_e32 v87, v87
	s_waitcnt lgkmcnt(4)
	v_mfma_f32_32x32x16_bf16 v[48:63], v[164:167], v[240:243], v[48:63]
	v_exp_f32_e32 v88, v88
	v_exp_f32_e32 v89, v89
	v_exp_f32_e32 v90, v90
	s_waitcnt lgkmcnt(2)
	v_mfma_f32_32x32x16_bf16 v[48:63], v[168:171], v[244:247], v[48:63]
	v_exp_f32_e32 v91, v91
	v_exp_f32_e32 v92, v92
	v_exp_f32_e32 v93, v93
	s_waitcnt lgkmcnt(0)
	v_mfma_f32_32x32x16_bf16 v[48:63], v[172:175], v[248:251], v[48:63]
	v_exp_f32_e32 v94, v94
	v_exp_f32_e32 v95, v95
	v_mov_b32_e32 v252, v207
	v_mov_b32_e32 v253, v208
	s_waitcnt lgkmcnt(0)
	s_barrier
; #define SBAR() __builtin_amdgcn_sched_barrier(0)
; #define SLOAD(i, k0) do { sr_[i].vs0 = LD8(&Vh[(long)((k0) + sr) * LDK + sc]); sr_[i].vs1 = LD8(&Vh[(long)((k0) + 32 + sr) * LDK + sc]); \
;     sr_[i].ks0 = LD8(&Kh[(long)((k0) + sr) * LDK + sc]); sr_[i].ks1 = LD8(&Kh[(long)((k0) + 32 + sr) * LDK + sc]); } while (0)
; __device__ __forceinline__ void finishSM(f32x16& p0, f32x16& p1, float alpha, float& l_reg, bf16x8& pa0, bf16x8& pa1, bf16x8& pa2, bf16x8& pa3) {
;     for (int r = 0; r < 16; ++r) p1[r] = __builtin_amdgcn_exp2f(p1[r]);
;     float ps = 0; for (int r = 0; r < 16; ++r) ps += p0[r]; for (int r = 0; r < 16; ++r) ps += p1[r];
;     { auto rr = __builtin_amdgcn_permlane32_swap(__float_as_uint(ps), __float_as_uint(ps), false, false);
;       ps = __uint_as_float(rr[0]) + __uint_as_float(rr[1]); }
;     l_reg = l_reg * alpha + ps;
;     ...
;     PK4(p0, 0, pa0); PK4(p0, 8, pa1); PK4(p1, 0, pa2); PK4(p1, 8, pa3);
;     ...
; }
; __device__ __forceinline__ void qkt(f32x16& p0, f32x16& p1, const bf16_t* Ks, const bf16x8* qr, int r32, int hi) {
;     p0 = f32x16{}; p1 = f32x16{};
;     for (int d0 = 0; d0 < 8; ++d0) { int cb = (d0 * 16 + hi * 8) * 2;
;         bf16x8 b0 = *reinterpret_cast<const bf16x8*>((const char*)Ks + KSWZ(r32, cb));
;         bf16x8 b1 = *reinterpret_cast<const bf16x8*>((const char*)Ks + KSWZ(32 + r32, cb));
;         p0 = __builtin_amdgcn_mfma_f32_32x32x16_bf16(b0, qr[d0], p0, 0, 0, 0);
;         p1 = __builtin_amdgcn_mfma_f32_32x32x16_bf16(b1, qr[d0], p1, 0, 0, 0); }
; }
; __device__ __forceinline__ void attn_body(const bf16_t* __restrict__ Qb, const bf16_t* __restrict__ Kh, const bf16_t* __restrict__ Vh, const bf16_t* __restrict__ Zb, ...
;     ...
;         SBAR(); qkt(pA0, pA1, K_lds, qr, r32, hi);
;         finishSM(pB0, pB1, 1.f, l_reg, pa0, pa1, pa2, pa3); SBAR();
;         SLOAD(SE, ((j + 3 < NT) ? (j + 3) : (NT - 1)) * KVBLK); SBAR();
;         pv_d0(o, vb0 + (int)SHM_V, pa0, pa1, pa2, pa3); partialSM(pA0, pA1, negBC);
	ds_read_b128 v[236:239], v211 offset:32768
	ds_read_b128 v[240:243], v211 offset:40960
	ds_read_b128 v[244:247], v212 offset:32768
	ds_read_b128 v[248:251], v212 offset:40960
	v_add_f32_e32 v219, v181, v221
	v_cvt_pk_bf16_f32 v160, v181, v221
	v_add_f32_e32 v219, v222, v219
	s_waitcnt lgkmcnt(3)
	v_mfma_f32_32x32x16_bf16 v[96:111], v[236:239], v[116:119], 0
	v_cvt_pk_bf16_f32 v161, v222, v223
	v_add_f32_e32 v219, v223, v219
	v_cvt_pk_bf16_f32 v162, v224, v225
	v_add_f32_e32 v219, v224, v219
	v_cvt_pk_bf16_f32 v163, v226, v227
	s_waitcnt lgkmcnt(2)
	v_mfma_f32_32x32x16_bf16 v[64:79], v[240:243], v[116:119], 0
	ds_read_b128 v[236:239], v213 offset:32768
	ds_read_b128 v[240:243], v213 offset:40960
	v_add_f32_e32 v219, v225, v219
	v_cvt_pk_bf16_f32 v164, v228, v229
	v_add_f32_e32 v219, v226, v219
	v_cvt_pk_bf16_f32 v165, v230, v231
	v_add_f32_e32 v219, v227, v219
	s_waitcnt lgkmcnt(3)
	v_mfma_f32_32x32x16_bf16 v[96:111], v[244:247], v[124:127], v[96:111]
	v_cvt_pk_bf16_f32 v166, v232, v233
	v_add_f32_e32 v219, v228, v219
	v_cvt_pk_bf16_f32 v167, v234, v235
	v_add_f32_e32 v219, v229, v219
	s_waitcnt lgkmcnt(2)
	v_mfma_f32_32x32x16_bf16 v[64:79], v[248:251], v[124:127], v[64:79]
	ds_read_b128 v[244:247], v214 offset:32768
	ds_read_b128 v[248:251], v214 offset:40960
	v_cvt_pk_bf16_f32 v168, v80, v81
	v_add_f32_e32 v219, v230, v219
	v_cvt_pk_bf16_f32 v169, v82, v83
	v_add_f32_e32 v219, v231, v219
	s_waitcnt lgkmcnt(3)
	v_mfma_f32_32x32x16_bf16 v[96:111], v[236:239], v[112:115], v[96:111]
	v_cvt_pk_bf16_f32 v170, v84, v85
	v_add_f32_e32 v219, v232, v219
	v_cvt_pk_bf16_f32 v171, v86, v87
	v_add_f32_e32 v219, v233, v219
	s_waitcnt lgkmcnt(2)
	v_mfma_f32_32x32x16_bf16 v[64:79], v[240:243], v[112:115], v[64:79]
	ds_read_b128 v[236:239], v215 offset:32768
	ds_read_b128 v[240:243], v215 offset:40960
	v_cvt_pk_bf16_f32 v172, v88, v89
	v_add_f32_e32 v219, v234, v219
	v_cvt_pk_bf16_f32 v173, v90, v91
	v_add_f32_e32 v219, v235, v219
	s_waitcnt lgkmcnt(3)
	v_mfma_f32_32x32x16_bf16 v[96:111], v[244:247], v[120:123], v[96:111]
	v_cvt_pk_bf16_f32 v174, v92, v93
	v_add_f32_e32 v219, v80, v219
	v_cvt_pk_bf16_f32 v175, v94, v95
	v_add_f32_e32 v219, v81, v219
	s_waitcnt lgkmcnt(2)
	v_mfma_f32_32x32x16_bf16 v[64:79], v[248:251], v[120:123], v[64:79]
	ds_read_b128 v[244:247], v216 offset:32768
	ds_read_b128 v[248:251], v216 offset:40960
	v_permlane32_swap_b32_e32 v160, v162
	v_add_f32_e32 v219, v82, v219
	s_waitcnt lgkmcnt(3)
	v_mfma_f32_32x32x16_bf16 v[96:111], v[236:239], v[132:135], v[96:111]
	v_permlane32_swap_b32_e32 v161, v163
	v_add_f32_e32 v219, v83, v219
	v_permlane32_swap_b32_e32 v164, v166
	s_waitcnt lgkmcnt(2)
	v_mfma_f32_32x32x16_bf16 v[64:79], v[240:243], v[132:135], v[64:79]
	ds_read_b128 v[236:239], v217 offset:32768
	ds_read_b128 v[240:243], v217 offset:40960
	v_add_f32_e32 v219, v84, v219
	v_permlane32_swap_b32_e32 v165, v167
	v_add_f32_e32 v219, v85, v219
	s_waitcnt lgkmcnt(3)
	v_mfma_f32_32x32x16_bf16 v[96:111], v[244:247], v[140:143], v[96:111]
	v_permlane32_swap_b32_e32 v168, v170
	v_add_f32_e32 v219, v86, v219
	s_waitcnt lgkmcnt(2)
	v_mfma_f32_32x32x16_bf16 v[64:79], v[248:251], v[140:143], v[64:79]
	ds_read_b128 v[244:247], v218 offset:32768
	ds_read_b128 v[248:251], v218 offset:40960
	v_permlane32_swap_b32_e32 v169, v171
	v_add_f32_e32 v219, v87, v219
	v_permlane32_swap_b32_e32 v172, v174
	s_waitcnt lgkmcnt(3)
	v_mfma_f32_32x32x16_bf16 v[96:111], v[236:239], v[128:131], v[96:111]
	v_add_f32_e32 v219, v88, v219
	v_permlane32_swap_b32_e32 v173, v175
	v_add_f32_e32 v219, v89, v219
	s_waitcnt lgkmcnt(2)
	v_mfma_f32_32x32x16_bf16 v[64:79], v[240:243], v[128:131], v[64:79]
	ds_read_b64_tr_b16 v[236:237], v205 offset:0
	ds_read_b64_tr_b16 v[238:239], v205 offset:2048
	ds_read_b64_tr_b16 v[240:241], v205 offset:4096
	ds_read_b64_tr_b16 v[242:243], v205 offset:6144
	v_add_f32_e32 v219, v90, v219
	v_add_f32_e32 v219, v91, v219
	v_add_f32_e32 v219, v92, v219
	v_add_f32_e32 v219, v93, v219
	s_waitcnt lgkmcnt(5)
	v_mfma_f32_32x32x16_bf16 v[96:111], v[244:247], v[136:139], v[96:111]
	v_add_f32_e32 v219, v94, v219
	v_add_f32_e32 v219, v95, v219
	v_mov_b32_e32 v220, v219
	s_nop 1
	s_waitcnt lgkmcnt(4)
	v_mfma_f32_32x32x16_bf16 v[64:79], v[248:251], v[136:139], v[64:79]
	v_permlane32_swap_b32_e32 v219, v220
	v_add_f32_e32 v219, v219, v220
	v_add_f32_e32 v204, v204, v219
	ds_read_b64_tr_b16 v[244:245], v205 offset:8192
	ds_read_b64_tr_b16 v[246:247], v205 offset:10240
	ds_read_b64_tr_b16 v[248:249], v205 offset:12288
	ds_read_b64_tr_b16 v[250:251], v205 offset:14336
	s_and_b64 vcc, exec, s[6:7]
	s_cbranch_vccz .Lat2_shift_B

; __device__ __forceinline__ void partialSM(f32x16& p0, f32x16& p1, float shift) {
;     if (shift != 0.f) { for (int r = 0; r < 16; ++r) { p0[r] += shift; p1[r] += shift; } }
;     for (int r = 0; r < 16; ++r) p0[r] = __builtin_amdgcn_exp2f(p0[r]);
.Lat2_shift_A:
	s_nop 15
	v_pk_add_f32 v[110:111], v[182:183], v[110:111]
	v_pk_add_f32 v[108:109], v[182:183], v[108:109]
	v_pk_add_f32 v[106:107], v[182:183], v[106:107]
	v_pk_add_f32 v[104:105], v[182:183], v[104:105]
	v_pk_add_f32 v[102:103], v[182:183], v[102:103]
	v_pk_add_f32 v[100:101], v[182:183], v[100:101]
	v_pk_add_f32 v[98:99], v[182:183], v[98:99]
	v_pk_add_f32 v[96:97], v[182:183], v[96:97]
	v_pk_add_f32 v[94:95], v[182:183], v[94:95]
	v_pk_add_f32 v[92:93], v[182:183], v[92:93]
	v_pk_add_f32 v[90:91], v[182:183], v[90:91]
	v_pk_add_f32 v[88:89], v[182:183], v[88:89]
	v_pk_add_f32 v[86:87], v[182:183], v[86:87]
	v_pk_add_f32 v[84:85], v[182:183], v[84:85]
	v_pk_add_f32 v[82:83], v[182:183], v[82:83]
	v_pk_add_f32 v[80:81], v[182:183], v[80:81]
	s_branch .Lat2_noshift_A
.Lat2_shift_B:
	s_nop 15
	v_pk_add_f32 v[110:111], v[182:183], v[110:111]
	v_pk_add_f32 v[108:109], v[182:183], v[108:109]
	v_pk_add_f32 v[106:107], v[182:183], v[106:107]
	v_pk_add_f32 v[104:105], v[182:183], v[104:105]
	v_pk_add_f32 v[102:103], v[182:183], v[102:103]
	v_pk_add_f32 v[100:101], v[182:183], v[100:101]
	v_pk_add_f32 v[98:99], v[182:183], v[98:99]
	v_pk_add_f32 v[96:97], v[182:183], v[96:97]
	v_pk_add_f32 v[78:79], v[182:183], v[78:79]
	v_pk_add_f32 v[76:77], v[182:183], v[76:77]
	v_pk_add_f32 v[74:75], v[182:183], v[74:75]
	v_pk_add_f32 v[72:73], v[182:183], v[72:73]
	v_pk_add_f32 v[70:71], v[182:183], v[70:71]
	v_pk_add_f32 v[68:69], v[182:183], v[68:69]
	v_pk_add_f32 v[66:67], v[182:183], v[66:67]
	v_pk_add_f32 v[64:65], v[182:183], v[64:65]
	s_branch .Lat2_noshift_B
